# priority: mid-segment s_setprio 0/1 flip pair removed from every MFMA segment (priority stays raised for all 32 MFMAs), on top of v24
# baseline (speedup 1.0000x reference)
; #define PG8_STAGE(bufoff, gbase, voff) do { _Pragma("unroll") for (int _i = 0; _i < 2; ++_i) \
;         __builtin_amdgcn_global_load_lds((const unsigned*)((const char*)(gbase) + (voff)[_i]), (LAS unsigned*)(lds + (bufoff) + ldsw + _i * 8192), 16, 0, 0); } while (0)
; #define PG8_LDA(dst, b, h) do { _Pragma("unroll") for (int m = 0; m < 4; ++m) _Pragma("unroll") for (int k = 0; k < 2; ++k) dst[m][k] = *(const LAS bf16x8*)(lds + PG8_SA(b, h) + aoff + m * 2048 + k * 1024); } while (0)
; #define PG8_LDB(dst, b, h) do { _Pragma("unroll") for (int n = 0; n < 2; ++n) _Pragma("unroll") for (int k = 0; k < 2; ++k) dst[n][k] = *(const LAS bf16x8*)(lds + PG8_SB(b, h) + boff + n * 2048 + k * 1024); } while (0)
; #define PG8_MMA(ai, bj, At, Bt) do { __builtin_amdgcn_s_setprio(1); _Pragma("unroll") for (int m = 0; m < 4; ++m) _Pragma("unroll") for (int n = 0; n < 2; ++n) _Pragma("unroll") for (int k = 0; k < 2; ++k) \
;         acc[ai][bj][m][n] = __builtin_amdgcn_mfma_f32_16x16x32_bf16(Bt[n][k], At[m][k], acc[ai][bj][m][n], 0, 0, 0); __builtin_amdgcn_s_setprio(0); } while (0)
; #define PG8_WAIT_V(n) asm volatile("s_waitcnt vmcnt(" #n ")" ::: "memory")
; #define PG8_WAIT_L(n) asm volatile("s_waitcnt lgkmcnt(" #n ")" ::: "memory")
; #define PG8_BAR __builtin_amdgcn_s_barrier()
; #define PG8_SCHED __builtin_amdgcn_sched_barrier(0)
; template <class Epi, class Sched>
; __device__ __forceinline__ void gemm_stream(LAS unsigned char* lds, const int lda, const int ldb, const Sched& S, const Epi& E, const int wv) {
;     ...
;             const char* a1 = cA + (size_t)(t + 1) * kstep;
;             const char* a2 = last ? nA : cA + (size_t)(t + 2) * kstep; const char* b2 = last ? nB : cB + (size_t)(t + 2) * kstep;
;             const char* a3 = a2 + kstep; const char* b3 = b2 + kstep;
;             PG8_LDB(B0, 0, 0); PG8_LDB(B1, 0, 1); PG8_SCHED; PG8_LDA(At, 0, 0); PG8_STAGE(PG8_SA(1, 1), a1 + hstepA, voffA);
;             PG8_WAIT_V(8); PG8_WAIT_L(0); PG8_BAR; PG8_MMA(0, 0, At, B0); PG8_MMA(0, 1, At, B1); PG8_BAR; PG8_SCHED;
;             PG8_LDA(At, 0, 1); PG8_STAGE(PG8_SB(0, 0), b2, voffB); PG8_STAGE(PG8_SB(0, 1), b2 + hstepB, voffB); PG8_STAGE(PG8_SA(0, 0), a2, voffA);
;             PG8_WAIT_V(8); PG8_WAIT_L(0); PG8_BAR; PG8_MMA(1, 0, At, B0); PG8_MMA(1, 1, At, B1); PG8_BAR; PG8_SCHED;
.LBB0_222:
	s_add_u32 s30, s28, 0xfff80080
	s_addc_u32 s31, s29, -1
	s_add_i32 s38, 0, 0x10000
	s_cmp_eq_u32 s37, 28
	s_cselect_b32 s35, s3, s31
	s_cselect_b32 s34, s21, s30
	s_cselect_b32 s31, s23, s36
	s_cselect_b32 s30, s27, s33
	s_add_i32 s59, 0, 0x14000
	v_add_u32_e32 v140, s38, v163
	v_add_u32_e32 v160, s59, v163
	ds_read_b128 v[128:131], v140
	ds_read_b128 v[132:135], v140 offset:1024
	ds_read_b128 v[136:139], v140 offset:2048
	ds_read_b128 v[140:143], v140 offset:3072
	ds_read_b128 v[156:159], v160
	ds_read_b128 v[166:169], v160 offset:1024
	ds_read_b128 v[170:173], v160 offset:2048
	ds_read_b128 v[174:177], v160 offset:3072
	v_lshl_add_u64 v[160:161], s[28:29], 0, v[152:153]
	s_add_i32 m0, s42, 0xc000
	ds_read_b128 v[178:181], v164
	ds_read_b128 v[182:185], v164 offset:1024
	ds_read_b128 v[186:189], v164 offset:2048
	ds_read_b128 v[190:193], v164 offset:3072
	ds_read_b128 v[200:203], v164 offset:4096
	ds_read_b128 v[204:207], v164 offset:5120
	ds_read_b128 v[208:211], v164 offset:6144
	ds_read_b128 v[212:215], v164 offset:7168
	global_load_lds_dwordx4 v[160:161], off
	v_lshl_add_u64 v[160:161], s[28:29], 0, v[154:155]
	s_add_i32 m0, s42, 0xe000
	s_nop 0
	global_load_lds_dwordx4 v[160:161], off
	s_waitcnt vmcnt(8)
	s_waitcnt lgkmcnt(0)
	s_barrier
	s_setprio 1
	v_mfma_f32_16x16x32_bf16 v[124:127], v[128:131], v[178:181], v[124:127]
	v_mfma_f32_16x16x32_bf16 v[120:123], v[136:139], v[178:181], v[120:123]
	v_mfma_f32_16x16x32_bf16 v[108:111], v[128:131], v[186:189], v[108:111]
	v_mfma_f32_16x16x32_bf16 v[104:107], v[136:139], v[186:189], v[104:107]
	v_mfma_f32_16x16x32_bf16 v[92:95], v[128:131], v[200:203], v[92:95]
	v_mfma_f32_16x16x32_bf16 v[88:91], v[136:139], v[200:203], v[88:91]
	v_mfma_f32_16x16x32_bf16 v[76:79], v[128:131], v[208:211], v[76:79]
	v_mfma_f32_16x16x32_bf16 v[72:75], v[136:139], v[208:211], v[72:75]
	v_mfma_f32_16x16x32_bf16 v[124:127], v[132:135], v[182:185], v[124:127]
	v_mfma_f32_16x16x32_bf16 v[120:123], v[140:143], v[182:185], v[120:123]
	v_mfma_f32_16x16x32_bf16 v[108:111], v[132:135], v[190:193], v[108:111]
	v_mfma_f32_16x16x32_bf16 v[104:107], v[140:143], v[190:193], v[104:107]
	v_mfma_f32_16x16x32_bf16 v[92:95], v[132:135], v[204:207], v[92:95]
	v_mfma_f32_16x16x32_bf16 v[88:91], v[140:143], v[204:207], v[88:91]
	v_mfma_f32_16x16x32_bf16 v[76:79], v[132:135], v[212:215], v[76:79]
	v_mfma_f32_16x16x32_bf16 v[72:75], v[140:143], v[212:215], v[72:75]
	v_mfma_f32_16x16x32_bf16 v[116:119], v[156:159], v[178:181], v[116:119]
	v_mfma_f32_16x16x32_bf16 v[112:115], v[170:173], v[178:181], v[112:115]
	v_mfma_f32_16x16x32_bf16 v[100:103], v[156:159], v[186:189], v[100:103]
	v_mfma_f32_16x16x32_bf16 v[96:99], v[170:173], v[186:189], v[96:99]
	v_mfma_f32_16x16x32_bf16 v[84:87], v[156:159], v[200:203], v[84:87]
	v_mfma_f32_16x16x32_bf16 v[80:83], v[170:173], v[200:203], v[80:83]
	v_mfma_f32_16x16x32_bf16 v[68:71], v[156:159], v[208:211], v[68:71]
	v_mfma_f32_16x16x32_bf16 v[64:67], v[170:173], v[208:211], v[64:67]
	v_mfma_f32_16x16x32_bf16 v[116:119], v[166:169], v[182:185], v[116:119]
	v_mfma_f32_16x16x32_bf16 v[112:115], v[174:177], v[182:185], v[112:115]
	v_mfma_f32_16x16x32_bf16 v[100:103], v[166:169], v[190:193], v[100:103]
	v_mfma_f32_16x16x32_bf16 v[96:99], v[174:177], v[190:193], v[96:99]
	v_mfma_f32_16x16x32_bf16 v[84:87], v[166:169], v[204:207], v[84:87]
	v_mfma_f32_16x16x32_bf16 v[80:83], v[174:177], v[204:207], v[80:83]
	v_mfma_f32_16x16x32_bf16 v[68:71], v[166:169], v[212:215], v[68:71]
	v_mfma_f32_16x16x32_bf16 v[64:67], v[174:177], v[212:215], v[64:67]
	s_setprio 0
	s_barrier
	s_add_i32 s38, s38, s41
	v_lshl_add_u64 v[160:161], s[30:31], 0, v[146:147]
	s_mov_b32 m0, s38
	ds_read_b128 v[178:181], v164 offset:16384
	ds_read_b128 v[182:185], v164 offset:17408
	ds_read_b128 v[186:189], v164 offset:18432
	ds_read_b128 v[190:193], v164 offset:19456
	ds_read_b128 v[200:203], v164 offset:20480
	ds_read_b128 v[204:207], v164 offset:21504
	ds_read_b128 v[208:211], v164 offset:22528
	ds_read_b128 v[212:215], v164 offset:23552
	global_load_lds_dwordx4 v[160:161], off
	s_add_i32 m0, s38, 0x2000
	s_add_u32 s38, s30, 0x20000
	v_lshl_add_u64 v[216:217], s[30:31], 0, v[150:151]
	s_addc_u32 s39, s31, 0
	s_add_i32 s59, s59, s41
	global_load_lds_dwordx4 v[216:217], off
	v_lshl_add_u64 v[218:219], s[38:39], 0, v[146:147]
	s_mov_b32 m0, s59
	v_lshl_add_u64 v[220:221], s[34:35], 0, v[148:149]
	global_load_lds_dwordx4 v[218:219], off
	v_lshl_add_u64 v[218:219], s[38:39], 0, v[150:151]
	s_add_i32 m0, s59, 0x2000
	s_nop 0
	global_load_lds_dwordx4 v[218:219], off
	v_lshl_add_u64 v[218:219], s[34:35], 0, v[144:145]
	s_mov_b32 m0, s42
	s_nop 0
	global_load_lds_dwordx4 v[218:219], off
	s_mov_b32 m0, s43
	s_nop 0
	global_load_lds_dwordx4 v[220:221], off
	s_waitcnt vmcnt(8)
	s_waitcnt lgkmcnt(0)
	s_barrier
; #define PG8_STAGE(bufoff, gbase, voff) do { _Pragma("unroll") for (int _i = 0; _i < 2; ++_i) \
;         __builtin_amdgcn_global_load_lds((const unsigned*)((const char*)(gbase) + (voff)[_i]), (LAS unsigned*)(lds + (bufoff) + ldsw + _i * 8192), 16, 0, 0); } while (0)
; #define PG8_LDA(dst, b, h) do { _Pragma("unroll") for (int m = 0; m < 4; ++m) _Pragma("unroll") for (int k = 0; k < 2; ++k) dst[m][k] = *(const LAS bf16x8*)(lds + PG8_SA(b, h) + aoff + m * 2048 + k * 1024); } while (0)
; #define PG8_LDB(dst, b, h) do { _Pragma("unroll") for (int n = 0; n < 2; ++n) _Pragma("unroll") for (int k = 0; k < 2; ++k) dst[n][k] = *(const LAS bf16x8*)(lds + PG8_SB(b, h) + boff + n * 2048 + k * 1024); } while (0)
; #define PG8_MMA(ai, bj, At, Bt) do { __builtin_amdgcn_s_setprio(1); _Pragma("unroll") for (int m = 0; m < 4; ++m) _Pragma("unroll") for (int n = 0; n < 2; ++n) _Pragma("unroll") for (int k = 0; k < 2; ++k) \
;         acc[ai][bj][m][n] = __builtin_amdgcn_mfma_f32_16x16x32_bf16(Bt[n][k], At[m][k], acc[ai][bj][m][n], 0, 0, 0); __builtin_amdgcn_s_setprio(0); } while (0)
; #define PG8_WAIT_V(n) asm volatile("s_waitcnt vmcnt(" #n ")" ::: "memory")
; #define PG8_WAIT_L(n) asm volatile("s_waitcnt lgkmcnt(" #n ")" ::: "memory")
; #define PG8_BAR __builtin_amdgcn_s_barrier()
; #define PG8_SCHED __builtin_amdgcn_sched_barrier(0)
; template <class Epi, class Sched>
; __device__ __forceinline__ void gemm_stream(LAS unsigned char* lds, const int lda, const int ldb, const Sched& S, const Epi& E, const int wv) {
;     ...
;             PG8_WAIT_V(8); PG8_WAIT_L(0); PG8_BAR; PG8_MMA(1, 0, At, B0); PG8_MMA(1, 1, At, B1); PG8_BAR; PG8_SCHED;
;             PG8_LDB(B0, 1, 0); PG8_LDB(B1, 1, 1); PG8_SCHED; PG8_LDA(At, 1, 0); PG8_STAGE(PG8_SA(0, 1), a2 + hstepA, voffA);
;             PG8_WAIT_V(8); PG8_WAIT_L(0); PG8_BAR; PG8_MMA(0, 0, At, B0); PG8_MMA(0, 1, At, B1); PG8_BAR; PG8_SCHED;
	s_setprio 1
	v_mfma_f32_16x16x32_bf16 v[60:63], v[128:131], v[178:181], v[60:63]
	v_mfma_f32_16x16x32_bf16 v[56:59], v[136:139], v[178:181], v[56:59]
	v_mfma_f32_16x16x32_bf16 v[44:47], v[128:131], v[186:189], v[44:47]
	v_mfma_f32_16x16x32_bf16 v[40:43], v[136:139], v[186:189], v[40:43]
	v_mfma_f32_16x16x32_bf16 v[28:31], v[128:131], v[200:203], v[28:31]
	v_mfma_f32_16x16x32_bf16 v[24:27], v[136:139], v[200:203], v[24:27]
	v_mfma_f32_16x16x32_bf16 v[12:15], v[128:131], v[208:211], v[12:15]
	v_mfma_f32_16x16x32_bf16 v[8:11], v[136:139], v[208:211], v[8:11]
	v_mfma_f32_16x16x32_bf16 v[60:63], v[132:135], v[182:185], v[60:63]
	v_mfma_f32_16x16x32_bf16 v[56:59], v[140:143], v[182:185], v[56:59]
	v_mfma_f32_16x16x32_bf16 v[44:47], v[132:135], v[190:193], v[44:47]
	v_mfma_f32_16x16x32_bf16 v[40:43], v[140:143], v[190:193], v[40:43]
	v_mfma_f32_16x16x32_bf16 v[28:31], v[132:135], v[204:207], v[28:31]
	v_mfma_f32_16x16x32_bf16 v[24:27], v[140:143], v[204:207], v[24:27]
	v_mfma_f32_16x16x32_bf16 v[12:15], v[132:135], v[212:215], v[12:15]
	v_mfma_f32_16x16x32_bf16 v[8:11], v[140:143], v[212:215], v[8:11]
	v_mfma_f32_16x16x32_bf16 v[52:55], v[156:159], v[178:181], v[52:55]
	v_mfma_f32_16x16x32_bf16 v[48:51], v[170:173], v[178:181], v[48:51]
	v_mfma_f32_16x16x32_bf16 v[36:39], v[156:159], v[186:189], v[36:39]
	v_mfma_f32_16x16x32_bf16 v[32:35], v[170:173], v[186:189], v[32:35]
	v_mfma_f32_16x16x32_bf16 v[20:23], v[156:159], v[200:203], v[20:23]
	v_mfma_f32_16x16x32_bf16 v[16:19], v[170:173], v[200:203], v[16:19]
	v_mfma_f32_16x16x32_bf16 v[4:7], v[156:159], v[208:211], v[4:7]
	v_mfma_f32_16x16x32_bf16 v[0:3], v[170:173], v[208:211], v[0:3]
	v_mfma_f32_16x16x32_bf16 v[52:55], v[166:169], v[182:185], v[52:55]
	v_mfma_f32_16x16x32_bf16 v[48:51], v[174:177], v[182:185], v[48:51]
	v_mfma_f32_16x16x32_bf16 v[36:39], v[166:169], v[190:193], v[36:39]
	v_mfma_f32_16x16x32_bf16 v[32:35], v[174:177], v[190:193], v[32:35]
	v_mfma_f32_16x16x32_bf16 v[20:23], v[166:169], v[204:207], v[20:23]
	v_mfma_f32_16x16x32_bf16 v[16:19], v[174:177], v[204:207], v[16:19]
	v_mfma_f32_16x16x32_bf16 v[4:7], v[166:169], v[212:215], v[4:7]
	v_mfma_f32_16x16x32_bf16 v[0:3], v[174:177], v[212:215], v[0:3]
	s_setprio 0
	s_barrier
	s_add_i32 s38, 0, 0x18000
	s_add_i32 s39, 0, 0x1c000
	v_add_u32_e32 v140, s38, v163
	v_add_u32_e32 v165, s39, v163
	ds_read_b128 v[128:131], v140
	ds_read_b128 v[132:135], v140 offset:1024
	ds_read_b128 v[136:139], v140 offset:2048
	ds_read_b128 v[140:143], v140 offset:3072
	ds_read_b128 v[156:159], v165
	ds_read_b128 v[166:169], v165 offset:1024
	ds_read_b128 v[170:173], v165 offset:2048
	ds_read_b128 v[174:177], v165 offset:3072
	s_add_u32 s34, s34, 0x80000
	s_addc_u32 s35, s35, 0
	s_mov_b32 m0, s44
	v_lshl_add_u64 v[222:223], s[34:35], 0, v[144:145]
	ds_read_b128 v[178:181], v164 offset:32768
	ds_read_b128 v[182:185], v164 offset:33792
	ds_read_b128 v[186:189], v164 offset:34816
	ds_read_b128 v[190:193], v164 offset:35840
	ds_read_b128 v[200:203], v164 offset:36864
	ds_read_b128 v[204:207], v164 offset:37888
	ds_read_b128 v[208:211], v164 offset:38912
	ds_read_b128 v[212:215], v164 offset:39936
	global_load_lds_dwordx4 v[222:223], off
	v_lshl_add_u64 v[222:223], s[34:35], 0, v[148:149]
	s_mov_b32 m0, s45
	s_nop 0
	global_load_lds_dwordx4 v[222:223], off
	s_waitcnt vmcnt(8)
	s_waitcnt lgkmcnt(0)
	s_barrier
	s_setprio 1
	v_mfma_f32_16x16x32_bf16 v[124:127], v[128:131], v[178:181], v[124:127]
	v_mfma_f32_16x16x32_bf16 v[120:123], v[136:139], v[178:181], v[120:123]
	v_mfma_f32_16x16x32_bf16 v[108:111], v[128:131], v[186:189], v[108:111]
	v_mfma_f32_16x16x32_bf16 v[104:107], v[136:139], v[186:189], v[104:107]
	v_mfma_f32_16x16x32_bf16 v[92:95], v[128:131], v[200:203], v[92:95]
	v_mfma_f32_16x16x32_bf16 v[88:91], v[136:139], v[200:203], v[88:91]
	v_mfma_f32_16x16x32_bf16 v[76:79], v[128:131], v[208:211], v[76:79]
	v_mfma_f32_16x16x32_bf16 v[72:75], v[136:139], v[208:211], v[72:75]
	v_mfma_f32_16x16x32_bf16 v[124:127], v[132:135], v[182:185], v[124:127]
	v_mfma_f32_16x16x32_bf16 v[120:123], v[140:143], v[182:185], v[120:123]
	v_mfma_f32_16x16x32_bf16 v[108:111], v[132:135], v[190:193], v[108:111]
	v_mfma_f32_16x16x32_bf16 v[104:107], v[140:143], v[190:193], v[104:107]
	v_mfma_f32_16x16x32_bf16 v[92:95], v[132:135], v[204:207], v[92:95]
	v_mfma_f32_16x16x32_bf16 v[88:91], v[140:143], v[204:207], v[88:91]
	v_mfma_f32_16x16x32_bf16 v[76:79], v[132:135], v[212:215], v[76:79]
	v_mfma_f32_16x16x32_bf16 v[72:75], v[140:143], v[212:215], v[72:75]
	v_mfma_f32_16x16x32_bf16 v[116:119], v[156:159], v[178:181], v[116:119]
	v_mfma_f32_16x16x32_bf16 v[112:115], v[170:173], v[178:181], v[112:115]
	v_mfma_f32_16x16x32_bf16 v[100:103], v[156:159], v[186:189], v[100:103]
	v_mfma_f32_16x16x32_bf16 v[96:99], v[170:173], v[186:189], v[96:99]
	v_mfma_f32_16x16x32_bf16 v[84:87], v[156:159], v[200:203], v[84:87]
	v_mfma_f32_16x16x32_bf16 v[80:83], v[170:173], v[200:203], v[80:83]
	v_mfma_f32_16x16x32_bf16 v[68:71], v[156:159], v[208:211], v[68:71]
	v_mfma_f32_16x16x32_bf16 v[64:67], v[170:173], v[208:211], v[64:67]
	v_mfma_f32_16x16x32_bf16 v[116:119], v[166:169], v[182:185], v[116:119]
	v_mfma_f32_16x16x32_bf16 v[112:115], v[174:177], v[182:185], v[112:115]
	v_mfma_f32_16x16x32_bf16 v[100:103], v[166:169], v[190:193], v[100:103]
	v_mfma_f32_16x16x32_bf16 v[96:99], v[174:177], v[190:193], v[96:99]
	v_mfma_f32_16x16x32_bf16 v[84:87], v[166:169], v[204:207], v[84:87]
	v_mfma_f32_16x16x32_bf16 v[80:83], v[174:177], v[204:207], v[80:83]
	v_mfma_f32_16x16x32_bf16 v[68:71], v[166:169], v[212:215], v[68:71]
	v_mfma_f32_16x16x32_bf16 v[64:67], v[174:177], v[212:215], v[64:67]
	s_setprio 0
	s_barrier
; #define PG8_STAGE(bufoff, gbase, voff) do { _Pragma("unroll") for (int _i = 0; _i < 2; ++_i) \
;         __builtin_amdgcn_global_load_lds((const unsigned*)((const char*)(gbase) + (voff)[_i]), (LAS unsigned*)(lds + (bufoff) + ldsw + _i * 8192), 16, 0, 0); } while (0)
; #define PG8_LDA(dst, b, h) do { _Pragma("unroll") for (int m = 0; m < 4; ++m) _Pragma("unroll") for (int k = 0; k < 2; ++k) dst[m][k] = *(const LAS bf16x8*)(lds + PG8_SA(b, h) + aoff + m * 2048 + k * 1024); } while (0)
; #define PG8_MMA(ai, bj, At, Bt) do { __builtin_amdgcn_s_setprio(1); _Pragma("unroll") for (int m = 0; m < 4; ++m) _Pragma("unroll") for (int n = 0; n < 2; ++n) _Pragma("unroll") for (int k = 0; k < 2; ++k) \
;         acc[ai][bj][m][n] = __builtin_amdgcn_mfma_f32_16x16x32_bf16(Bt[n][k], At[m][k], acc[ai][bj][m][n], 0, 0, 0); __builtin_amdgcn_s_setprio(0); } while (0)
; #define PG8_WAIT_V(n) asm volatile("s_waitcnt vmcnt(" #n ")" ::: "memory")
; #define PG8_WAIT_L(n) asm volatile("s_waitcnt lgkmcnt(" #n ")" ::: "memory")
; #define PG8_BAR __builtin_amdgcn_s_barrier()
; #define PG8_SCHED __builtin_amdgcn_sched_barrier(0)
; template <class Epi, class Sched>
; __device__ __forceinline__ void gemm_stream(LAS unsigned char* lds, const int lda, const int ldb, const Sched& S, const Epi& E, const int wv) {
;     ...
;             PG8_LDA(At, 1, 1); PG8_STAGE(PG8_SB(1, 0), b3, voffB); PG8_STAGE(PG8_SB(1, 1), b3 + hstepB, voffB); PG8_STAGE(PG8_SA(1, 0), a3, voffA);
;             PG8_WAIT_V(8); PG8_WAIT_L(0); PG8_BAR; PG8_MMA(1, 0, At, B0); PG8_MMA(1, 1, At, B1); PG8_BAR; PG8_SCHED;
;         }
;         if (wr == 0) PG8_BAR;
	s_add_i32 s34, s38, s41
	v_lshl_add_u64 v[160:161], v[160:161], 0, s[78:79]
	s_mov_b32 m0, s34
	ds_read_b128 v[178:181], v164 offset:49152
	ds_read_b128 v[182:185], v164 offset:50176
	ds_read_b128 v[186:189], v164 offset:51200
	ds_read_b128 v[190:193], v164 offset:52224
	ds_read_b128 v[200:203], v164 offset:53248
	ds_read_b128 v[204:207], v164 offset:54272
	ds_read_b128 v[208:211], v164 offset:55296
	ds_read_b128 v[212:215], v164 offset:56320
	global_load_lds_dwordx4 v[160:161], off
	s_add_i32 m0, s34, 0x2000
	s_add_u32 s30, s30, 0x20080
	v_lshl_add_u64 v[160:161], v[216:217], 0, s[78:79]
	s_addc_u32 s31, s31, 0
	s_add_i32 s34, s39, s41
	global_load_lds_dwordx4 v[160:161], off
	v_lshl_add_u64 v[160:161], s[30:31], 0, v[146:147]
	s_mov_b32 m0, s34
	s_nop 0
	global_load_lds_dwordx4 v[160:161], off
	v_lshl_add_u64 v[160:161], s[30:31], 0, v[150:151]
	s_add_i32 m0, s34, 0x2000
	s_nop 0
	global_load_lds_dwordx4 v[160:161], off
	v_lshl_add_u64 v[160:161], v[218:219], 0, s[78:79]
	s_mov_b32 m0, s49
	s_nop 0
	global_load_lds_dwordx4 v[160:161], off
	v_lshl_add_u64 v[160:161], v[220:221], 0, s[78:79]
	s_mov_b32 m0, s50
	s_nop 0
	global_load_lds_dwordx4 v[160:161], off
	s_waitcnt vmcnt(8)
	s_waitcnt lgkmcnt(0)
	s_barrier
	s_setprio 1
	v_mfma_f32_16x16x32_bf16 v[60:63], v[128:131], v[178:181], v[60:63]
	v_mfma_f32_16x16x32_bf16 v[56:59], v[136:139], v[178:181], v[56:59]
	v_mfma_f32_16x16x32_bf16 v[44:47], v[128:131], v[186:189], v[44:47]
	v_mfma_f32_16x16x32_bf16 v[40:43], v[136:139], v[186:189], v[40:43]
	v_mfma_f32_16x16x32_bf16 v[28:31], v[128:131], v[200:203], v[28:31]
	v_mfma_f32_16x16x32_bf16 v[24:27], v[136:139], v[200:203], v[24:27]
	v_mfma_f32_16x16x32_bf16 v[12:15], v[128:131], v[208:211], v[12:15]
	v_mfma_f32_16x16x32_bf16 v[8:11], v[136:139], v[208:211], v[8:11]
	v_mfma_f32_16x16x32_bf16 v[60:63], v[132:135], v[182:185], v[60:63]
	v_mfma_f32_16x16x32_bf16 v[56:59], v[140:143], v[182:185], v[56:59]
	v_mfma_f32_16x16x32_bf16 v[44:47], v[132:135], v[190:193], v[44:47]
	v_mfma_f32_16x16x32_bf16 v[40:43], v[140:143], v[190:193], v[40:43]
	v_mfma_f32_16x16x32_bf16 v[28:31], v[132:135], v[204:207], v[28:31]
	v_mfma_f32_16x16x32_bf16 v[24:27], v[140:143], v[204:207], v[24:27]
	v_mfma_f32_16x16x32_bf16 v[12:15], v[132:135], v[212:215], v[12:15]
	v_mfma_f32_16x16x32_bf16 v[8:11], v[140:143], v[212:215], v[8:11]
	v_mfma_f32_16x16x32_bf16 v[52:55], v[156:159], v[178:181], v[52:55]
	v_mfma_f32_16x16x32_bf16 v[48:51], v[170:173], v[178:181], v[48:51]
	v_mfma_f32_16x16x32_bf16 v[36:39], v[156:159], v[186:189], v[36:39]
	v_mfma_f32_16x16x32_bf16 v[32:35], v[170:173], v[186:189], v[32:35]
	v_mfma_f32_16x16x32_bf16 v[20:23], v[156:159], v[200:203], v[20:23]
	v_mfma_f32_16x16x32_bf16 v[16:19], v[170:173], v[200:203], v[16:19]
	v_mfma_f32_16x16x32_bf16 v[4:7], v[156:159], v[208:211], v[4:7]
	v_mfma_f32_16x16x32_bf16 v[0:3], v[170:173], v[208:211], v[0:3]
	v_mfma_f32_16x16x32_bf16 v[52:55], v[166:169], v[182:185], v[52:55]
	v_mfma_f32_16x16x32_bf16 v[48:51], v[174:177], v[182:185], v[48:51]
	v_mfma_f32_16x16x32_bf16 v[36:39], v[166:169], v[190:193], v[36:39]
	v_mfma_f32_16x16x32_bf16 v[32:35], v[174:177], v[190:193], v[32:35]
	v_mfma_f32_16x16x32_bf16 v[20:23], v[166:169], v[204:207], v[20:23]
	v_mfma_f32_16x16x32_bf16 v[16:19], v[174:177], v[204:207], v[16:19]
	v_mfma_f32_16x16x32_bf16 v[4:7], v[166:169], v[212:215], v[4:7]
	v_mfma_f32_16x16x32_bf16 v[0:3], v[174:177], v[212:215], v[0:3]
	s_setprio 0
	s_barrier
	s_add_i32 s37, s37, 2
	s_add_u32 s28, s28, 0x100
	s_addc_u32 s29, s29, 0
	s_add_u32 s33, s33, 0x100
	s_addc_u32 s36, s36, 0
	s_cmp_gt_u32 s37, 29
	s_cbranch_scc0 .LBB0_222
	s_and_b64 vcc, exec, s[14:15]
	s_cbranch_vccz .LBB0_225
	s_barrier

; #define PG8_STAGE(bufoff, gbase, voff) do { _Pragma("unroll") for (int _i = 0; _i < 2; ++_i) \
;         __builtin_amdgcn_global_load_lds((const unsigned*)((const char*)(gbase) + (voff)[_i]), (LAS unsigned*)(lds + (bufoff) + ldsw + _i * 8192), 16, 0, 0); } while (0)
; #define PG8_LDA(dst, b, h) do { _Pragma("unroll") for (int m = 0; m < 4; ++m) _Pragma("unroll") for (int k = 0; k < 2; ++k) dst[m][k] = *(const LAS bf16x8*)(lds + PG8_SA(b, h) + aoff + m * 2048 + k * 1024); } while (0)
; #define PG8_LDB(dst, b, h) do { _Pragma("unroll") for (int n = 0; n < 2; ++n) _Pragma("unroll") for (int k = 0; k < 2; ++k) dst[n][k] = *(const LAS bf16x8*)(lds + PG8_SB(b, h) + boff + n * 2048 + k * 1024); } while (0)
; #define PG8_MMA(ai, bj, At, Bt) do { __builtin_amdgcn_s_setprio(1); _Pragma("unroll") for (int m = 0; m < 4; ++m) _Pragma("unroll") for (int n = 0; n < 2; ++n) _Pragma("unroll") for (int k = 0; k < 2; ++k) \
;         acc[ai][bj][m][n] = __builtin_amdgcn_mfma_f32_16x16x32_bf16(Bt[n][k], At[m][k], acc[ai][bj][m][n], 0, 0, 0); __builtin_amdgcn_s_setprio(0); } while (0)
; #define PG8_WAIT_V(n) asm volatile("s_waitcnt vmcnt(" #n ")" ::: "memory")
; #define PG8_WAIT_L(n) asm volatile("s_waitcnt lgkmcnt(" #n ")" ::: "memory")
; #define PG8_BAR __builtin_amdgcn_s_barrier()
; #define PG8_SCHED __builtin_amdgcn_sched_barrier(0)
; template <class Epi, class Sched>
; __device__ __forceinline__ void gemm_stream(LAS unsigned char* lds, const int lda, const int ldb, const Sched& S, const Epi& E, const int wv) {
;     ...
;             const char* a1 = cA + (size_t)(t + 1) * kstep;
;             const char* a2 = last ? nA : cA + (size_t)(t + 2) * kstep; const char* b2 = last ? nB : cB + (size_t)(t + 2) * kstep;
;             const char* a3 = a2 + kstep; const char* b3 = b2 + kstep;
;             PG8_LDB(B0, 0, 0); PG8_LDB(B1, 0, 1); PG8_SCHED; PG8_LDA(At, 0, 0); PG8_STAGE(PG8_SA(1, 1), a1 + hstepA, voffA);
;             PG8_WAIT_V(8); PG8_WAIT_L(0); PG8_BAR; PG8_MMA(0, 0, At, B0); PG8_MMA(0, 1, At, B1); PG8_BAR; PG8_SCHED;
;             PG8_LDA(At, 0, 1); PG8_STAGE(PG8_SB(0, 0), b2, voffB); PG8_STAGE(PG8_SB(0, 1), b2 + hstepB, voffB); PG8_STAGE(PG8_SA(0, 0), a2, voffA);
;             PG8_WAIT_V(8); PG8_WAIT_L(0); PG8_BAR; PG8_MMA(1, 0, At, B0); PG8_MMA(1, 1, At, B1); PG8_BAR; PG8_SCHED;
.LBB0_496:
	s_add_i32 s63, s24, 2
	s_add_u32 s22, s4, 0x100
	s_addc_u32 s23, s5, 0
	s_add_i32 s66, 0, 0x10000
	s_cmp_eq_u32 s60, s24
	s_cselect_b32 s27, s33, s23
	s_cselect_b32 s26, s57, s22
	v_add_u32_e32 v120, s66, v235
	s_cselect_b32 s25, s58, s62
	s_cselect_b32 s24, s59, s61
	s_add_i32 s67, 0, 0x14000
	ds_read_b128 v[130:133], v120
	ds_read_b128 v[134:137], v120 offset:1024
	ds_read_b128 v[138:141], v120 offset:2048
	ds_read_b128 v[142:145], v120 offset:3072
	v_add_u32_e32 v120, s67, v235
	ds_read_b128 v[146:149], v120
	ds_read_b128 v[150:153], v120 offset:1024
	ds_read_b128 v[154:157], v120 offset:2048
	ds_read_b128 v[158:161], v120 offset:3072
	v_lshl_add_u64 v[120:121], s[4:5], 0, v[208:209]
	s_add_i32 m0, s36, 0xc000
	ds_read_b128 v[162:165], v236
	ds_read_b128 v[166:169], v236 offset:1024
	ds_read_b128 v[170:173], v236 offset:2048
	ds_read_b128 v[174:177], v236 offset:3072
	ds_read_b128 v[178:181], v236 offset:4096
	ds_read_b128 v[182:185], v236 offset:5120
	ds_read_b128 v[186:189], v236 offset:6144
	ds_read_b128 v[190:193], v236 offset:7168
	global_load_lds_dwordx4 v[120:121], off
	v_lshl_add_u64 v[120:121], s[4:5], 0, v[210:211]
	s_add_i32 m0, s36, 0xe000
	s_nop 0
	global_load_lds_dwordx4 v[120:121], off
	s_waitcnt vmcnt(8)
	s_waitcnt lgkmcnt(0)
	s_barrier
	s_setprio 1
	v_mfma_f32_16x16x32_bf16 v[126:129], v[130:133], v[162:165], v[126:129]
	v_mfma_f32_16x16x32_bf16 v[120:123], v[138:141], v[162:165], v[122:125]
	v_mfma_f32_16x16x32_bf16 v[116:119], v[130:133], v[170:173], v[116:119]
	v_mfma_f32_16x16x32_bf16 v[112:115], v[138:141], v[170:173], v[112:115]
	v_mfma_f32_16x16x32_bf16 v[100:103], v[130:133], v[178:181], v[100:103]
	v_mfma_f32_16x16x32_bf16 v[96:99], v[138:141], v[178:181], v[96:99]
	v_mfma_f32_16x16x32_bf16 v[84:87], v[130:133], v[186:189], v[84:87]
	v_mfma_f32_16x16x32_bf16 v[80:83], v[138:141], v[186:189], v[80:83]
	v_mfma_f32_16x16x32_bf16 v[126:129], v[134:137], v[166:169], v[126:129]
	v_mfma_f32_16x16x32_bf16 v[120:123], v[142:145], v[166:169], v[120:123]
	v_mfma_f32_16x16x32_bf16 v[116:119], v[134:137], v[174:177], v[116:119]
	v_mfma_f32_16x16x32_bf16 v[112:115], v[142:145], v[174:177], v[112:115]
	v_mfma_f32_16x16x32_bf16 v[100:103], v[134:137], v[182:185], v[100:103]
	v_mfma_f32_16x16x32_bf16 v[96:99], v[142:145], v[182:185], v[96:99]
	v_mfma_f32_16x16x32_bf16 v[84:87], v[134:137], v[190:193], v[84:87]
	v_mfma_f32_16x16x32_bf16 v[80:83], v[142:145], v[190:193], v[80:83]
	v_mfma_f32_16x16x32_bf16 v[108:111], v[146:149], v[162:165], v[108:111]
	v_mfma_f32_16x16x32_bf16 v[104:107], v[154:157], v[162:165], v[104:107]
	v_mfma_f32_16x16x32_bf16 v[92:95], v[146:149], v[170:173], v[92:95]
	v_mfma_f32_16x16x32_bf16 v[88:91], v[154:157], v[170:173], v[88:91]
	v_mfma_f32_16x16x32_bf16 v[76:79], v[146:149], v[178:181], v[76:79]
	v_mfma_f32_16x16x32_bf16 v[72:75], v[154:157], v[178:181], v[72:75]
	v_mfma_f32_16x16x32_bf16 v[68:71], v[146:149], v[186:189], v[68:71]
	v_mfma_f32_16x16x32_bf16 v[64:67], v[154:157], v[186:189], v[64:67]
	v_mfma_f32_16x16x32_bf16 v[108:111], v[150:153], v[166:169], v[108:111]
	v_mfma_f32_16x16x32_bf16 v[104:107], v[158:161], v[166:169], v[104:107]
	v_mfma_f32_16x16x32_bf16 v[92:95], v[150:153], v[174:177], v[92:95]
	v_mfma_f32_16x16x32_bf16 v[88:91], v[158:161], v[174:177], v[88:91]
	v_mfma_f32_16x16x32_bf16 v[76:79], v[150:153], v[182:185], v[76:79]
	v_mfma_f32_16x16x32_bf16 v[72:75], v[158:161], v[182:185], v[72:75]
	v_mfma_f32_16x16x32_bf16 v[68:71], v[150:153], v[190:193], v[68:71]
	v_mfma_f32_16x16x32_bf16 v[64:67], v[158:161], v[190:193], v[64:67]
	s_setprio 0
	s_barrier
	s_add_i32 s4, s66, s35
	v_lshl_add_u64 v[196:197], s[24:25], 0, v[202:203]
	s_mov_b32 m0, s4
	ds_read_b128 v[162:165], v236 offset:16384
	ds_read_b128 v[166:169], v236 offset:17408
	ds_read_b128 v[170:173], v236 offset:18432
	ds_read_b128 v[174:177], v236 offset:19456
	ds_read_b128 v[178:181], v236 offset:20480
	ds_read_b128 v[182:185], v236 offset:21504
	ds_read_b128 v[186:189], v236 offset:22528
	ds_read_b128 v[190:193], v236 offset:23552
	global_load_lds_dwordx4 v[196:197], off
	s_add_i32 m0, s4, 0x2000
	s_add_u32 s4, s24, 0x20000
	v_lshl_add_u64 v[198:199], s[24:25], 0, v[206:207]
	s_addc_u32 s5, s25, 0
	s_add_i32 s66, s67, s35
	global_load_lds_dwordx4 v[198:199], off
	v_lshl_add_u64 v[124:125], s[4:5], 0, v[202:203]
	s_mov_b32 m0, s66
	v_lshl_add_u64 v[212:213], s[26:27], 0, v[200:201]
	global_load_lds_dwordx4 v[124:125], off
	v_lshl_add_u64 v[124:125], s[4:5], 0, v[206:207]
	s_add_i32 m0, s66, 0x2000
	v_lshl_add_u64 v[214:215], s[26:27], 0, v[204:205]
	global_load_lds_dwordx4 v[124:125], off
	s_mov_b32 m0, s36
	s_nop 0
	global_load_lds_dwordx4 v[212:213], off
	s_mov_b32 m0, s37
	s_nop 0
	global_load_lds_dwordx4 v[214:215], off
	s_waitcnt vmcnt(8)
	s_waitcnt lgkmcnt(0)
	s_barrier
; #define PG8_STAGE(bufoff, gbase, voff) do { _Pragma("unroll") for (int _i = 0; _i < 2; ++_i) \
;         __builtin_amdgcn_global_load_lds((const unsigned*)((const char*)(gbase) + (voff)[_i]), (LAS unsigned*)(lds + (bufoff) + ldsw + _i * 8192), 16, 0, 0); } while (0)
; #define PG8_LDA(dst, b, h) do { _Pragma("unroll") for (int m = 0; m < 4; ++m) _Pragma("unroll") for (int k = 0; k < 2; ++k) dst[m][k] = *(const LAS bf16x8*)(lds + PG8_SA(b, h) + aoff + m * 2048 + k * 1024); } while (0)
; #define PG8_LDB(dst, b, h) do { _Pragma("unroll") for (int n = 0; n < 2; ++n) _Pragma("unroll") for (int k = 0; k < 2; ++k) dst[n][k] = *(const LAS bf16x8*)(lds + PG8_SB(b, h) + boff + n * 2048 + k * 1024); } while (0)
; #define PG8_MMA(ai, bj, At, Bt) do { __builtin_amdgcn_s_setprio(1); _Pragma("unroll") for (int m = 0; m < 4; ++m) _Pragma("unroll") for (int n = 0; n < 2; ++n) _Pragma("unroll") for (int k = 0; k < 2; ++k) \
;         acc[ai][bj][m][n] = __builtin_amdgcn_mfma_f32_16x16x32_bf16(Bt[n][k], At[m][k], acc[ai][bj][m][n], 0, 0, 0); __builtin_amdgcn_s_setprio(0); } while (0)
; #define PG8_WAIT_V(n) asm volatile("s_waitcnt vmcnt(" #n ")" ::: "memory")
; #define PG8_WAIT_L(n) asm volatile("s_waitcnt lgkmcnt(" #n ")" ::: "memory")
; #define PG8_BAR __builtin_amdgcn_s_barrier()
; #define PG8_SCHED __builtin_amdgcn_sched_barrier(0)
; template <class Epi, class Sched>
; __device__ __forceinline__ void gemm_stream(LAS unsigned char* lds, const int lda, const int ldb, const Sched& S, const Epi& E, const int wv) {
;     ...
;             PG8_WAIT_V(8); PG8_WAIT_L(0); PG8_BAR; PG8_MMA(1, 0, At, B0); PG8_MMA(1, 1, At, B1); PG8_BAR; PG8_SCHED;
;             PG8_LDB(B0, 1, 0); PG8_LDB(B1, 1, 1); PG8_SCHED; PG8_LDA(At, 1, 0); PG8_STAGE(PG8_SA(0, 1), a2 + hstepA, voffA);
;             PG8_WAIT_V(8); PG8_WAIT_L(0); PG8_BAR; PG8_MMA(0, 0, At, B0); PG8_MMA(0, 1, At, B1); PG8_BAR; PG8_SCHED;
	s_setprio 1
	v_mfma_f32_16x16x32_bf16 v[60:63], v[130:133], v[162:165], v[60:63]
	v_mfma_f32_16x16x32_bf16 v[56:59], v[138:141], v[162:165], v[56:59]
	v_mfma_f32_16x16x32_bf16 v[52:55], v[130:133], v[170:173], v[52:55]
	v_mfma_f32_16x16x32_bf16 v[48:51], v[138:141], v[170:173], v[48:51]
	v_mfma_f32_16x16x32_bf16 v[36:39], v[130:133], v[178:181], v[36:39]
	v_mfma_f32_16x16x32_bf16 v[32:35], v[138:141], v[178:181], v[32:35]
	v_mfma_f32_16x16x32_bf16 v[20:23], v[130:133], v[186:189], v[20:23]
	v_mfma_f32_16x16x32_bf16 v[16:19], v[138:141], v[186:189], v[16:19]
	v_mfma_f32_16x16x32_bf16 v[60:63], v[134:137], v[166:169], v[60:63]
	v_mfma_f32_16x16x32_bf16 v[56:59], v[142:145], v[166:169], v[56:59]
	v_mfma_f32_16x16x32_bf16 v[52:55], v[134:137], v[174:177], v[52:55]
	v_mfma_f32_16x16x32_bf16 v[48:51], v[142:145], v[174:177], v[48:51]
	v_mfma_f32_16x16x32_bf16 v[36:39], v[134:137], v[182:185], v[36:39]
	v_mfma_f32_16x16x32_bf16 v[32:35], v[142:145], v[182:185], v[32:35]
	v_mfma_f32_16x16x32_bf16 v[20:23], v[134:137], v[190:193], v[20:23]
	v_mfma_f32_16x16x32_bf16 v[16:19], v[142:145], v[190:193], v[16:19]
	v_mfma_f32_16x16x32_bf16 v[44:47], v[146:149], v[162:165], v[44:47]
	v_mfma_f32_16x16x32_bf16 v[40:43], v[154:157], v[162:165], v[40:43]
	v_mfma_f32_16x16x32_bf16 v[28:31], v[146:149], v[170:173], v[28:31]
	v_mfma_f32_16x16x32_bf16 v[24:27], v[154:157], v[170:173], v[24:27]
	v_mfma_f32_16x16x32_bf16 v[12:15], v[146:149], v[178:181], v[12:15]
	v_mfma_f32_16x16x32_bf16 v[8:11], v[154:157], v[178:181], v[8:11]
	v_mfma_f32_16x16x32_bf16 v[4:7], v[146:149], v[186:189], v[4:7]
	v_mfma_f32_16x16x32_bf16 v[0:3], v[154:157], v[186:189], v[0:3]
	v_mfma_f32_16x16x32_bf16 v[44:47], v[150:153], v[166:169], v[44:47]
	v_mfma_f32_16x16x32_bf16 v[40:43], v[158:161], v[166:169], v[40:43]
	v_mfma_f32_16x16x32_bf16 v[28:31], v[150:153], v[174:177], v[28:31]
	v_mfma_f32_16x16x32_bf16 v[24:27], v[158:161], v[174:177], v[24:27]
	v_mfma_f32_16x16x32_bf16 v[12:15], v[150:153], v[182:185], v[12:15]
	v_mfma_f32_16x16x32_bf16 v[8:11], v[158:161], v[182:185], v[8:11]
	v_mfma_f32_16x16x32_bf16 v[4:7], v[150:153], v[190:193], v[4:7]
	v_mfma_f32_16x16x32_bf16 v[0:3], v[158:161], v[190:193], v[0:3]
	s_setprio 0
	s_barrier
	s_add_i32 s66, 0, 0x18000
	v_add_u32_e32 v124, s66, v235
	s_add_i32 s67, 0, 0x1c000
	ds_read_b128 v[130:133], v124
	ds_read_b128 v[134:137], v124 offset:1024
	ds_read_b128 v[138:141], v124 offset:2048
	ds_read_b128 v[142:145], v124 offset:3072
	v_add_u32_e32 v124, s67, v235
	ds_read_b128 v[146:149], v124
	ds_read_b128 v[150:153], v124 offset:1024
	ds_read_b128 v[154:157], v124 offset:2048
	ds_read_b128 v[158:161], v124 offset:3072
	s_add_u32 s4, s26, 0x480000
	s_addc_u32 s5, s27, 0
	s_mov_b32 m0, s38
	v_lshl_add_u64 v[124:125], s[4:5], 0, v[200:201]
	ds_read_b128 v[162:165], v236 offset:32768
	ds_read_b128 v[166:169], v236 offset:33792
	ds_read_b128 v[170:173], v236 offset:34816
	ds_read_b128 v[174:177], v236 offset:35840
	ds_read_b128 v[178:181], v236 offset:36864
	ds_read_b128 v[182:185], v236 offset:37888
	ds_read_b128 v[186:189], v236 offset:38912
	ds_read_b128 v[190:193], v236 offset:39936
	global_load_lds_dwordx4 v[124:125], off
	v_lshl_add_u64 v[124:125], s[4:5], 0, v[204:205]
	s_mov_b32 m0, s39
	s_nop 0
	global_load_lds_dwordx4 v[124:125], off
	s_waitcnt vmcnt(8)
	s_waitcnt lgkmcnt(0)
	s_barrier
	s_setprio 1
	v_mfma_f32_16x16x32_bf16 v[124:127], v[130:133], v[162:165], v[126:129]
	v_mfma_f32_16x16x32_bf16 v[120:123], v[138:141], v[162:165], v[120:123]
	v_mfma_f32_16x16x32_bf16 v[116:119], v[130:133], v[170:173], v[116:119]
	v_mfma_f32_16x16x32_bf16 v[112:115], v[138:141], v[170:173], v[112:115]
	v_mfma_f32_16x16x32_bf16 v[100:103], v[130:133], v[178:181], v[100:103]
	v_mfma_f32_16x16x32_bf16 v[96:99], v[138:141], v[178:181], v[96:99]
	v_mfma_f32_16x16x32_bf16 v[84:87], v[130:133], v[186:189], v[84:87]
	v_mfma_f32_16x16x32_bf16 v[80:83], v[138:141], v[186:189], v[80:83]
	v_mfma_f32_16x16x32_bf16 v[126:129], v[134:137], v[166:169], v[124:127]
	v_mfma_f32_16x16x32_bf16 v[122:125], v[142:145], v[166:169], v[120:123]
	v_mfma_f32_16x16x32_bf16 v[116:119], v[134:137], v[174:177], v[116:119]
	v_mfma_f32_16x16x32_bf16 v[112:115], v[142:145], v[174:177], v[112:115]
	v_mfma_f32_16x16x32_bf16 v[100:103], v[134:137], v[182:185], v[100:103]
	v_mfma_f32_16x16x32_bf16 v[96:99], v[142:145], v[182:185], v[96:99]
	v_mfma_f32_16x16x32_bf16 v[84:87], v[134:137], v[190:193], v[84:87]
	v_mfma_f32_16x16x32_bf16 v[80:83], v[142:145], v[190:193], v[80:83]
	v_mfma_f32_16x16x32_bf16 v[108:111], v[146:149], v[162:165], v[108:111]
	v_mfma_f32_16x16x32_bf16 v[104:107], v[154:157], v[162:165], v[104:107]
	v_mfma_f32_16x16x32_bf16 v[92:95], v[146:149], v[170:173], v[92:95]
	v_mfma_f32_16x16x32_bf16 v[88:91], v[154:157], v[170:173], v[88:91]
	v_mfma_f32_16x16x32_bf16 v[76:79], v[146:149], v[178:181], v[76:79]
	v_mfma_f32_16x16x32_bf16 v[72:75], v[154:157], v[178:181], v[72:75]
	v_mfma_f32_16x16x32_bf16 v[68:71], v[146:149], v[186:189], v[68:71]
	v_mfma_f32_16x16x32_bf16 v[64:67], v[154:157], v[186:189], v[64:67]
	v_mfma_f32_16x16x32_bf16 v[108:111], v[150:153], v[166:169], v[108:111]
	v_mfma_f32_16x16x32_bf16 v[104:107], v[158:161], v[166:169], v[104:107]
	v_mfma_f32_16x16x32_bf16 v[92:95], v[150:153], v[174:177], v[92:95]
	v_mfma_f32_16x16x32_bf16 v[88:91], v[158:161], v[174:177], v[88:91]
	v_mfma_f32_16x16x32_bf16 v[76:79], v[150:153], v[182:185], v[76:79]
	v_mfma_f32_16x16x32_bf16 v[72:75], v[158:161], v[182:185], v[72:75]
	v_mfma_f32_16x16x32_bf16 v[68:71], v[150:153], v[190:193], v[68:71]
	v_mfma_f32_16x16x32_bf16 v[64:67], v[158:161], v[190:193], v[64:67]
	s_setprio 0
	s_barrier
; #define PG8_STAGE(bufoff, gbase, voff) do { _Pragma("unroll") for (int _i = 0; _i < 2; ++_i) \
;         __builtin_amdgcn_global_load_lds((const unsigned*)((const char*)(gbase) + (voff)[_i]), (LAS unsigned*)(lds + (bufoff) + ldsw + _i * 8192), 16, 0, 0); } while (0)
; #define PG8_LDA(dst, b, h) do { _Pragma("unroll") for (int m = 0; m < 4; ++m) _Pragma("unroll") for (int k = 0; k < 2; ++k) dst[m][k] = *(const LAS bf16x8*)(lds + PG8_SA(b, h) + aoff + m * 2048 + k * 1024); } while (0)
; #define PG8_MMA(ai, bj, At, Bt) do { __builtin_amdgcn_s_setprio(1); _Pragma("unroll") for (int m = 0; m < 4; ++m) _Pragma("unroll") for (int n = 0; n < 2; ++n) _Pragma("unroll") for (int k = 0; k < 2; ++k) \
;         acc[ai][bj][m][n] = __builtin_amdgcn_mfma_f32_16x16x32_bf16(Bt[n][k], At[m][k], acc[ai][bj][m][n], 0, 0, 0); __builtin_amdgcn_s_setprio(0); } while (0)
; #define PG8_WAIT_V(n) asm volatile("s_waitcnt vmcnt(" #n ")" ::: "memory")
; #define PG8_WAIT_L(n) asm volatile("s_waitcnt lgkmcnt(" #n ")" ::: "memory")
; #define PG8_BAR __builtin_amdgcn_s_barrier()
; #define PG8_SCHED __builtin_amdgcn_sched_barrier(0)
; template <class Epi, class Sched>
; __device__ __forceinline__ void gemm_stream(LAS unsigned char* lds, const int lda, const int ldb, const Sched& S, const Epi& E, const int wv) {
;     ...
;             PG8_LDA(At, 1, 1); PG8_STAGE(PG8_SB(1, 0), b3, voffB); PG8_STAGE(PG8_SB(1, 1), b3 + hstepB, voffB); PG8_STAGE(PG8_SA(1, 0), a3, voffA);
;             PG8_WAIT_V(8); PG8_WAIT_L(0); PG8_BAR; PG8_MMA(1, 0, At, B0); PG8_MMA(1, 1, At, B1); PG8_BAR; PG8_SCHED;
;         }
;         if (wr == 0) PG8_BAR;
	s_add_i32 s4, s66, s35
	v_lshl_add_u64 v[120:121], v[196:197], 0, s[78:79]
	s_mov_b32 m0, s4
	ds_read_b128 v[162:165], v236 offset:49152
	ds_read_b128 v[166:169], v236 offset:50176
	ds_read_b128 v[170:173], v236 offset:51200
	ds_read_b128 v[174:177], v236 offset:52224
	ds_read_b128 v[178:181], v236 offset:53248
	ds_read_b128 v[182:185], v236 offset:54272
	ds_read_b128 v[186:189], v236 offset:55296
	ds_read_b128 v[190:193], v236 offset:56320
	global_load_lds_dwordx4 v[120:121], off
	s_add_i32 m0, s4, 0x2000
	s_add_u32 s4, s24, 0x20080
	v_lshl_add_u64 v[120:121], v[198:199], 0, s[78:79]
	s_addc_u32 s5, s25, 0
	s_add_i32 s24, s67, s35
	global_load_lds_dwordx4 v[120:121], off
	v_lshl_add_u64 v[120:121], s[4:5], 0, v[202:203]
	s_mov_b32 m0, s24
	s_nop 0
	global_load_lds_dwordx4 v[120:121], off
	v_lshl_add_u64 v[120:121], s[4:5], 0, v[206:207]
	s_add_i32 m0, s24, 0x2000
	s_nop 0
	global_load_lds_dwordx4 v[120:121], off
	v_lshl_add_u64 v[120:121], v[212:213], 0, s[78:79]
	s_mov_b32 m0, s43
	s_nop 0
	global_load_lds_dwordx4 v[120:121], off
	v_lshl_add_u64 v[120:121], v[214:215], 0, s[78:79]
	s_mov_b32 m0, s44
	s_nop 0
	global_load_lds_dwordx4 v[120:121], off
	s_waitcnt vmcnt(8)
	s_waitcnt lgkmcnt(0)
	s_barrier
	s_setprio 1
	v_mfma_f32_16x16x32_bf16 v[60:63], v[130:133], v[162:165], v[60:63]
	v_mfma_f32_16x16x32_bf16 v[56:59], v[138:141], v[162:165], v[56:59]
	v_mfma_f32_16x16x32_bf16 v[52:55], v[130:133], v[170:173], v[52:55]
	v_mfma_f32_16x16x32_bf16 v[48:51], v[138:141], v[170:173], v[48:51]
	v_mfma_f32_16x16x32_bf16 v[36:39], v[130:133], v[178:181], v[36:39]
	v_mfma_f32_16x16x32_bf16 v[32:35], v[138:141], v[178:181], v[32:35]
	v_mfma_f32_16x16x32_bf16 v[20:23], v[130:133], v[186:189], v[20:23]
	v_mfma_f32_16x16x32_bf16 v[16:19], v[138:141], v[186:189], v[16:19]
	v_mfma_f32_16x16x32_bf16 v[60:63], v[134:137], v[166:169], v[60:63]
	v_mfma_f32_16x16x32_bf16 v[56:59], v[142:145], v[166:169], v[56:59]
	v_mfma_f32_16x16x32_bf16 v[52:55], v[134:137], v[174:177], v[52:55]
	v_mfma_f32_16x16x32_bf16 v[48:51], v[142:145], v[174:177], v[48:51]
	v_mfma_f32_16x16x32_bf16 v[36:39], v[134:137], v[182:185], v[36:39]
	v_mfma_f32_16x16x32_bf16 v[32:35], v[142:145], v[182:185], v[32:35]
	v_mfma_f32_16x16x32_bf16 v[20:23], v[134:137], v[190:193], v[20:23]
	v_mfma_f32_16x16x32_bf16 v[16:19], v[142:145], v[190:193], v[16:19]
	v_mfma_f32_16x16x32_bf16 v[44:47], v[146:149], v[162:165], v[44:47]
	v_mfma_f32_16x16x32_bf16 v[40:43], v[154:157], v[162:165], v[40:43]
	v_mfma_f32_16x16x32_bf16 v[28:31], v[146:149], v[170:173], v[28:31]
	v_mfma_f32_16x16x32_bf16 v[24:27], v[154:157], v[170:173], v[24:27]
	v_mfma_f32_16x16x32_bf16 v[12:15], v[146:149], v[178:181], v[12:15]
	v_mfma_f32_16x16x32_bf16 v[8:11], v[154:157], v[178:181], v[8:11]
	v_mfma_f32_16x16x32_bf16 v[4:7], v[146:149], v[186:189], v[4:7]
	v_mfma_f32_16x16x32_bf16 v[0:3], v[154:157], v[186:189], v[0:3]
	v_mfma_f32_16x16x32_bf16 v[44:47], v[150:153], v[166:169], v[44:47]
	v_mfma_f32_16x16x32_bf16 v[40:43], v[158:161], v[166:169], v[40:43]
	v_mfma_f32_16x16x32_bf16 v[28:31], v[150:153], v[174:177], v[28:31]
	v_mfma_f32_16x16x32_bf16 v[24:27], v[158:161], v[174:177], v[24:27]
	v_mfma_f32_16x16x32_bf16 v[12:15], v[150:153], v[182:185], v[12:15]
	v_mfma_f32_16x16x32_bf16 v[8:11], v[158:161], v[182:185], v[8:11]
	v_mfma_f32_16x16x32_bf16 v[4:7], v[150:153], v[190:193], v[4:7]
	v_mfma_f32_16x16x32_bf16 v[0:3], v[158:161], v[190:193], v[0:3]
	s_setprio 0
	s_barrier
	s_add_u32 s61, s61, 0x100
	s_addc_u32 s62, s62, 0
	s_cmp_ge_i32 s63, s56
	s_mov_b64 s[4:5], s[22:23]
	s_mov_b32 s24, s63
	s_cbranch_scc0 .LBB0_496
	v_mov_b32_e32 v244, 0x3d800000
	s_and_b64 vcc, exec, s[12:13]
	s_cbranch_vccz .LBB0_499
	s_barrier

; #define PG8_STAGE(bufoff, gbase, voff) do { _Pragma("unroll") for (int _i = 0; _i < 2; ++_i) \
;         __builtin_amdgcn_global_load_lds((const unsigned*)((const char*)(gbase) + (voff)[_i]), (LAS unsigned*)(lds + (bufoff) + ldsw + _i * 8192), 16, 0, 0); } while (0)
; #define PG8_LDA(dst, b, h) do { _Pragma("unroll") for (int m = 0; m < 4; ++m) _Pragma("unroll") for (int k = 0; k < 2; ++k) dst[m][k] = *(const LAS bf16x8*)(lds + PG8_SA(b, h) + aoff + m * 2048 + k * 1024); } while (0)
; #define PG8_LDB(dst, b, h) do { _Pragma("unroll") for (int n = 0; n < 2; ++n) _Pragma("unroll") for (int k = 0; k < 2; ++k) dst[n][k] = *(const LAS bf16x8*)(lds + PG8_SB(b, h) + boff + n * 2048 + k * 1024); } while (0)
; #define PG8_MMA(ai, bj, At, Bt) do { __builtin_amdgcn_s_setprio(1); _Pragma("unroll") for (int m = 0; m < 4; ++m) _Pragma("unroll") for (int n = 0; n < 2; ++n) _Pragma("unroll") for (int k = 0; k < 2; ++k) \
;         acc[ai][bj][m][n] = __builtin_amdgcn_mfma_f32_16x16x32_bf16(Bt[n][k], At[m][k], acc[ai][bj][m][n], 0, 0, 0); __builtin_amdgcn_s_setprio(0); } while (0)
; #define PG8_WAIT_V(n) asm volatile("s_waitcnt vmcnt(" #n ")" ::: "memory")
; #define PG8_WAIT_L(n) asm volatile("s_waitcnt lgkmcnt(" #n ")" ::: "memory")
; #define PG8_BAR __builtin_amdgcn_s_barrier()
; #define PG8_SCHED __builtin_amdgcn_sched_barrier(0)
; template <class Epi, class Sched>
; __device__ __forceinline__ void gemm_stream(LAS unsigned char* lds, const int lda, const int ldb, const Sched& S, const Epi& E, const int wv) {
;     ...
;             const char* a1 = cA + (size_t)(t + 1) * kstep;
;             const char* a2 = last ? nA : cA + (size_t)(t + 2) * kstep; const char* b2 = last ? nB : cB + (size_t)(t + 2) * kstep;
;             const char* a3 = a2 + kstep; const char* b3 = b2 + kstep;
;             PG8_LDB(B0, 0, 0); PG8_LDB(B1, 0, 1); PG8_SCHED; PG8_LDA(At, 0, 0); PG8_STAGE(PG8_SA(1, 1), a1 + hstepA, voffA);
;             PG8_WAIT_V(8); PG8_WAIT_L(0); PG8_BAR; PG8_MMA(0, 0, At, B0); PG8_MMA(0, 1, At, B1); PG8_BAR; PG8_SCHED;
;             PG8_LDA(At, 0, 1); PG8_STAGE(PG8_SB(0, 0), b2, voffB); PG8_STAGE(PG8_SB(0, 1), b2 + hstepB, voffB); PG8_STAGE(PG8_SA(0, 0), a2, voffA);
;             PG8_WAIT_V(8); PG8_WAIT_L(0); PG8_BAR; PG8_MMA(1, 0, At, B0); PG8_MMA(1, 1, At, B1); PG8_BAR; PG8_SCHED;
.LBB0_600:
	s_add_u32 s22, s20, 0xfff80080
	s_addc_u32 s23, s21, -1
	s_add_i32 s47, 0, 0x10000
	s_cmp_eq_u32 s46, 28
	s_cselect_b32 s25, s17, s23
	s_cselect_b32 s24, s16, s22
	s_cselect_b32 s23, s19, s15
	s_cselect_b32 s22, s18, s13
	s_add_i32 s50, 0, 0x14000
	v_add_u32_e32 v140, s47, v165
	v_add_u32_e32 v167, s50, v165
	ds_read_b128 v[128:131], v140
	ds_read_b128 v[132:135], v140 offset:1024
	ds_read_b128 v[136:139], v140 offset:2048
	ds_read_b128 v[140:143], v140 offset:3072
	ds_read_b128 v[156:159], v167
	ds_read_b128 v[160:163], v167 offset:1024
	ds_read_b128 v[168:171], v167 offset:2048
	ds_read_b128 v[172:175], v167 offset:3072
	v_lshl_add_u64 v[192:193], s[20:21], 0, v[152:153]
	s_add_i32 m0, s31, 0xc000
	ds_read_b128 v[176:179], v166
	ds_read_b128 v[180:183], v166 offset:1024
	ds_read_b128 v[184:187], v166 offset:2048
	ds_read_b128 v[188:191], v166 offset:3072
	ds_read_b128 v[200:203], v166 offset:4096
	ds_read_b128 v[204:207], v166 offset:5120
	ds_read_b128 v[208:211], v166 offset:6144
	ds_read_b128 v[212:215], v166 offset:7168
	global_load_lds_dwordx4 v[192:193], off
	v_lshl_add_u64 v[192:193], s[20:21], 0, v[154:155]
	s_add_i32 m0, s31, 0xe000
	s_nop 0
	global_load_lds_dwordx4 v[192:193], off
	s_waitcnt vmcnt(8)
	s_waitcnt lgkmcnt(0)
	s_barrier
	s_setprio 1
	v_mfma_f32_16x16x32_bf16 v[124:127], v[128:131], v[176:179], v[124:127]
	v_mfma_f32_16x16x32_bf16 v[120:123], v[136:139], v[176:179], v[120:123]
	v_mfma_f32_16x16x32_bf16 v[108:111], v[128:131], v[184:187], v[108:111]
	v_mfma_f32_16x16x32_bf16 v[104:107], v[136:139], v[184:187], v[104:107]
	v_mfma_f32_16x16x32_bf16 v[92:95], v[128:131], v[200:203], v[92:95]
	v_mfma_f32_16x16x32_bf16 v[88:91], v[136:139], v[200:203], v[88:91]
	v_mfma_f32_16x16x32_bf16 v[76:79], v[128:131], v[208:211], v[76:79]
	v_mfma_f32_16x16x32_bf16 v[72:75], v[136:139], v[208:211], v[72:75]
	v_mfma_f32_16x16x32_bf16 v[124:127], v[132:135], v[180:183], v[124:127]
	v_mfma_f32_16x16x32_bf16 v[120:123], v[140:143], v[180:183], v[120:123]
	v_mfma_f32_16x16x32_bf16 v[108:111], v[132:135], v[188:191], v[108:111]
	v_mfma_f32_16x16x32_bf16 v[104:107], v[140:143], v[188:191], v[104:107]
	v_mfma_f32_16x16x32_bf16 v[92:95], v[132:135], v[204:207], v[92:95]
	v_mfma_f32_16x16x32_bf16 v[88:91], v[140:143], v[204:207], v[88:91]
	v_mfma_f32_16x16x32_bf16 v[76:79], v[132:135], v[212:215], v[76:79]
	v_mfma_f32_16x16x32_bf16 v[72:75], v[140:143], v[212:215], v[72:75]
	v_mfma_f32_16x16x32_bf16 v[116:119], v[156:159], v[176:179], v[116:119]
	v_mfma_f32_16x16x32_bf16 v[112:115], v[168:171], v[176:179], v[112:115]
	v_mfma_f32_16x16x32_bf16 v[100:103], v[156:159], v[184:187], v[100:103]
	v_mfma_f32_16x16x32_bf16 v[96:99], v[168:171], v[184:187], v[96:99]
	v_mfma_f32_16x16x32_bf16 v[84:87], v[156:159], v[200:203], v[84:87]
	v_mfma_f32_16x16x32_bf16 v[80:83], v[168:171], v[200:203], v[80:83]
	v_mfma_f32_16x16x32_bf16 v[68:71], v[156:159], v[208:211], v[68:71]
	v_mfma_f32_16x16x32_bf16 v[64:67], v[168:171], v[208:211], v[64:67]
	v_mfma_f32_16x16x32_bf16 v[116:119], v[160:163], v[180:183], v[116:119]
	v_mfma_f32_16x16x32_bf16 v[112:115], v[172:175], v[180:183], v[112:115]
	v_mfma_f32_16x16x32_bf16 v[100:103], v[160:163], v[188:191], v[100:103]
	v_mfma_f32_16x16x32_bf16 v[96:99], v[172:175], v[188:191], v[96:99]
	v_mfma_f32_16x16x32_bf16 v[84:87], v[160:163], v[204:207], v[84:87]
	v_mfma_f32_16x16x32_bf16 v[80:83], v[172:175], v[204:207], v[80:83]
	v_mfma_f32_16x16x32_bf16 v[68:71], v[160:163], v[212:215], v[68:71]
	v_mfma_f32_16x16x32_bf16 v[64:67], v[172:175], v[212:215], v[64:67]
	s_setprio 0
	s_barrier
	s_add_i32 s47, s47, s30
	v_lshl_add_u64 v[192:193], s[22:23], 0, v[148:149]
	s_mov_b32 m0, s47
	ds_read_b128 v[176:179], v166 offset:16384
	ds_read_b128 v[180:183], v166 offset:17408
	ds_read_b128 v[184:187], v166 offset:18432
	ds_read_b128 v[188:191], v166 offset:19456
	ds_read_b128 v[200:203], v166 offset:20480
	ds_read_b128 v[204:207], v166 offset:21504
	ds_read_b128 v[208:211], v166 offset:22528
	ds_read_b128 v[212:215], v166 offset:23552
	global_load_lds_dwordx4 v[192:193], off
	s_add_i32 m0, s47, 0x2000
	s_add_u32 s48, s22, 0x20000
	v_lshl_add_u64 v[196:197], s[22:23], 0, v[144:145]
	s_addc_u32 s49, s23, 0
	s_add_i32 s47, s50, s30
	global_load_lds_dwordx4 v[196:197], off
	v_lshl_add_u64 v[198:199], s[48:49], 0, v[148:149]
	s_mov_b32 m0, s47
	v_lshl_add_u64 v[216:217], s[24:25], 0, v[146:147]
	global_load_lds_dwordx4 v[198:199], off
	v_lshl_add_u64 v[198:199], s[48:49], 0, v[144:145]
	s_add_i32 m0, s47, 0x2000
	s_nop 0
	global_load_lds_dwordx4 v[198:199], off
	v_lshl_add_u64 v[198:199], s[24:25], 0, v[150:151]
	s_mov_b32 m0, s31
	s_nop 0
	global_load_lds_dwordx4 v[198:199], off
	s_mov_b32 m0, s34
	s_nop 0
	global_load_lds_dwordx4 v[216:217], off
	s_waitcnt vmcnt(8)
	s_waitcnt lgkmcnt(0)
	s_barrier
; #define PG8_STAGE(bufoff, gbase, voff) do { _Pragma("unroll") for (int _i = 0; _i < 2; ++_i) \
;         __builtin_amdgcn_global_load_lds((const unsigned*)((const char*)(gbase) + (voff)[_i]), (LAS unsigned*)(lds + (bufoff) + ldsw + _i * 8192), 16, 0, 0); } while (0)
; #define PG8_LDA(dst, b, h) do { _Pragma("unroll") for (int m = 0; m < 4; ++m) _Pragma("unroll") for (int k = 0; k < 2; ++k) dst[m][k] = *(const LAS bf16x8*)(lds + PG8_SA(b, h) + aoff + m * 2048 + k * 1024); } while (0)
; #define PG8_LDB(dst, b, h) do { _Pragma("unroll") for (int n = 0; n < 2; ++n) _Pragma("unroll") for (int k = 0; k < 2; ++k) dst[n][k] = *(const LAS bf16x8*)(lds + PG8_SB(b, h) + boff + n * 2048 + k * 1024); } while (0)
; #define PG8_MMA(ai, bj, At, Bt) do { __builtin_amdgcn_s_setprio(1); _Pragma("unroll") for (int m = 0; m < 4; ++m) _Pragma("unroll") for (int n = 0; n < 2; ++n) _Pragma("unroll") for (int k = 0; k < 2; ++k) \
;         acc[ai][bj][m][n] = __builtin_amdgcn_mfma_f32_16x16x32_bf16(Bt[n][k], At[m][k], acc[ai][bj][m][n], 0, 0, 0); __builtin_amdgcn_s_setprio(0); } while (0)
; #define PG8_WAIT_V(n) asm volatile("s_waitcnt vmcnt(" #n ")" ::: "memory")
; #define PG8_WAIT_L(n) asm volatile("s_waitcnt lgkmcnt(" #n ")" ::: "memory")
; #define PG8_BAR __builtin_amdgcn_s_barrier()
; #define PG8_SCHED __builtin_amdgcn_sched_barrier(0)
; template <class Epi, class Sched>
; __device__ __forceinline__ void gemm_stream(LAS unsigned char* lds, const int lda, const int ldb, const Sched& S, const Epi& E, const int wv) {
;     ...
;             PG8_WAIT_V(8); PG8_WAIT_L(0); PG8_BAR; PG8_MMA(1, 0, At, B0); PG8_MMA(1, 1, At, B1); PG8_BAR; PG8_SCHED;
;             PG8_LDB(B0, 1, 0); PG8_LDB(B1, 1, 1); PG8_SCHED; PG8_LDA(At, 1, 0); PG8_STAGE(PG8_SA(0, 1), a2 + hstepA, voffA);
;             PG8_WAIT_V(8); PG8_WAIT_L(0); PG8_BAR; PG8_MMA(0, 0, At, B0); PG8_MMA(0, 1, At, B1); PG8_BAR; PG8_SCHED;
	s_setprio 1
	v_mfma_f32_16x16x32_bf16 v[60:63], v[128:131], v[176:179], v[60:63]
	v_mfma_f32_16x16x32_bf16 v[56:59], v[136:139], v[176:179], v[56:59]
	v_mfma_f32_16x16x32_bf16 v[44:47], v[128:131], v[184:187], v[44:47]
	v_mfma_f32_16x16x32_bf16 v[40:43], v[136:139], v[184:187], v[40:43]
	v_mfma_f32_16x16x32_bf16 v[28:31], v[128:131], v[200:203], v[28:31]
	v_mfma_f32_16x16x32_bf16 v[24:27], v[136:139], v[200:203], v[24:27]
	v_mfma_f32_16x16x32_bf16 v[12:15], v[128:131], v[208:211], v[12:15]
	v_mfma_f32_16x16x32_bf16 v[8:11], v[136:139], v[208:211], v[8:11]
	v_mfma_f32_16x16x32_bf16 v[60:63], v[132:135], v[180:183], v[60:63]
	v_mfma_f32_16x16x32_bf16 v[56:59], v[140:143], v[180:183], v[56:59]
	v_mfma_f32_16x16x32_bf16 v[44:47], v[132:135], v[188:191], v[44:47]
	v_mfma_f32_16x16x32_bf16 v[40:43], v[140:143], v[188:191], v[40:43]
	v_mfma_f32_16x16x32_bf16 v[28:31], v[132:135], v[204:207], v[28:31]
	v_mfma_f32_16x16x32_bf16 v[24:27], v[140:143], v[204:207], v[24:27]
	v_mfma_f32_16x16x32_bf16 v[12:15], v[132:135], v[212:215], v[12:15]
	v_mfma_f32_16x16x32_bf16 v[8:11], v[140:143], v[212:215], v[8:11]
	v_mfma_f32_16x16x32_bf16 v[52:55], v[156:159], v[176:179], v[52:55]
	v_mfma_f32_16x16x32_bf16 v[48:51], v[168:171], v[176:179], v[48:51]
	v_mfma_f32_16x16x32_bf16 v[36:39], v[156:159], v[184:187], v[36:39]
	v_mfma_f32_16x16x32_bf16 v[32:35], v[168:171], v[184:187], v[32:35]
	v_mfma_f32_16x16x32_bf16 v[20:23], v[156:159], v[200:203], v[20:23]
	v_mfma_f32_16x16x32_bf16 v[16:19], v[168:171], v[200:203], v[16:19]
	v_mfma_f32_16x16x32_bf16 v[4:7], v[156:159], v[208:211], v[4:7]
	v_mfma_f32_16x16x32_bf16 v[0:3], v[168:171], v[208:211], v[0:3]
	v_mfma_f32_16x16x32_bf16 v[52:55], v[160:163], v[180:183], v[52:55]
	v_mfma_f32_16x16x32_bf16 v[48:51], v[172:175], v[180:183], v[48:51]
	v_mfma_f32_16x16x32_bf16 v[36:39], v[160:163], v[188:191], v[36:39]
	v_mfma_f32_16x16x32_bf16 v[32:35], v[172:175], v[188:191], v[32:35]
	v_mfma_f32_16x16x32_bf16 v[20:23], v[160:163], v[204:207], v[20:23]
	v_mfma_f32_16x16x32_bf16 v[16:19], v[172:175], v[204:207], v[16:19]
	v_mfma_f32_16x16x32_bf16 v[4:7], v[160:163], v[212:215], v[4:7]
	v_mfma_f32_16x16x32_bf16 v[0:3], v[172:175], v[212:215], v[0:3]
	s_setprio 0
	s_barrier
	s_add_i32 s47, 0, 0x18000
	s_add_i32 s48, 0, 0x1c000
	v_add_u32_e32 v140, s47, v165
	v_add_u32_e32 v167, s48, v165
	ds_read_b128 v[128:131], v140
	ds_read_b128 v[132:135], v140 offset:1024
	ds_read_b128 v[136:139], v140 offset:2048
	ds_read_b128 v[140:143], v140 offset:3072
	ds_read_b128 v[156:159], v167
	ds_read_b128 v[160:163], v167 offset:1024
	ds_read_b128 v[168:171], v167 offset:2048
	ds_read_b128 v[172:175], v167 offset:3072
	s_add_u32 s24, s24, 0x80000
	s_addc_u32 s25, s25, 0
	s_mov_b32 m0, s35
	v_lshl_add_u64 v[218:219], s[24:25], 0, v[150:151]
	ds_read_b128 v[176:179], v166 offset:32768
	ds_read_b128 v[180:183], v166 offset:33792
	ds_read_b128 v[184:187], v166 offset:34816
	ds_read_b128 v[188:191], v166 offset:35840
	ds_read_b128 v[200:203], v166 offset:36864
	ds_read_b128 v[204:207], v166 offset:37888
	ds_read_b128 v[208:211], v166 offset:38912
	ds_read_b128 v[212:215], v166 offset:39936
	global_load_lds_dwordx4 v[218:219], off
	v_lshl_add_u64 v[218:219], s[24:25], 0, v[146:147]
	s_mov_b32 m0, s36
	s_nop 0
	global_load_lds_dwordx4 v[218:219], off
	s_waitcnt vmcnt(8)
	s_waitcnt lgkmcnt(0)
	s_barrier
	s_setprio 1
	v_mfma_f32_16x16x32_bf16 v[124:127], v[128:131], v[176:179], v[124:127]
	v_mfma_f32_16x16x32_bf16 v[120:123], v[136:139], v[176:179], v[120:123]
	v_mfma_f32_16x16x32_bf16 v[108:111], v[128:131], v[184:187], v[108:111]
	v_mfma_f32_16x16x32_bf16 v[104:107], v[136:139], v[184:187], v[104:107]
	v_mfma_f32_16x16x32_bf16 v[92:95], v[128:131], v[200:203], v[92:95]
	v_mfma_f32_16x16x32_bf16 v[88:91], v[136:139], v[200:203], v[88:91]
	v_mfma_f32_16x16x32_bf16 v[76:79], v[128:131], v[208:211], v[76:79]
	v_mfma_f32_16x16x32_bf16 v[72:75], v[136:139], v[208:211], v[72:75]
	v_mfma_f32_16x16x32_bf16 v[124:127], v[132:135], v[180:183], v[124:127]
	v_mfma_f32_16x16x32_bf16 v[120:123], v[140:143], v[180:183], v[120:123]
	v_mfma_f32_16x16x32_bf16 v[108:111], v[132:135], v[188:191], v[108:111]
	v_mfma_f32_16x16x32_bf16 v[104:107], v[140:143], v[188:191], v[104:107]
	v_mfma_f32_16x16x32_bf16 v[92:95], v[132:135], v[204:207], v[92:95]
	v_mfma_f32_16x16x32_bf16 v[88:91], v[140:143], v[204:207], v[88:91]
	v_mfma_f32_16x16x32_bf16 v[76:79], v[132:135], v[212:215], v[76:79]
	v_mfma_f32_16x16x32_bf16 v[72:75], v[140:143], v[212:215], v[72:75]
	v_mfma_f32_16x16x32_bf16 v[116:119], v[156:159], v[176:179], v[116:119]
	v_mfma_f32_16x16x32_bf16 v[112:115], v[168:171], v[176:179], v[112:115]
	v_mfma_f32_16x16x32_bf16 v[100:103], v[156:159], v[184:187], v[100:103]
	v_mfma_f32_16x16x32_bf16 v[96:99], v[168:171], v[184:187], v[96:99]
	v_mfma_f32_16x16x32_bf16 v[84:87], v[156:159], v[200:203], v[84:87]
	v_mfma_f32_16x16x32_bf16 v[80:83], v[168:171], v[200:203], v[80:83]
	v_mfma_f32_16x16x32_bf16 v[68:71], v[156:159], v[208:211], v[68:71]
	v_mfma_f32_16x16x32_bf16 v[64:67], v[168:171], v[208:211], v[64:67]
	v_mfma_f32_16x16x32_bf16 v[116:119], v[160:163], v[180:183], v[116:119]
	v_mfma_f32_16x16x32_bf16 v[112:115], v[172:175], v[180:183], v[112:115]
	v_mfma_f32_16x16x32_bf16 v[100:103], v[160:163], v[188:191], v[100:103]
	v_mfma_f32_16x16x32_bf16 v[96:99], v[172:175], v[188:191], v[96:99]
	v_mfma_f32_16x16x32_bf16 v[84:87], v[160:163], v[204:207], v[84:87]
	v_mfma_f32_16x16x32_bf16 v[80:83], v[172:175], v[204:207], v[80:83]
	v_mfma_f32_16x16x32_bf16 v[68:71], v[160:163], v[212:215], v[68:71]
	v_mfma_f32_16x16x32_bf16 v[64:67], v[172:175], v[212:215], v[64:67]
	s_setprio 0
	s_barrier
; #define PG8_STAGE(bufoff, gbase, voff) do { _Pragma("unroll") for (int _i = 0; _i < 2; ++_i) \
;         __builtin_amdgcn_global_load_lds((const unsigned*)((const char*)(gbase) + (voff)[_i]), (LAS unsigned*)(lds + (bufoff) + ldsw + _i * 8192), 16, 0, 0); } while (0)
; #define PG8_LDA(dst, b, h) do { _Pragma("unroll") for (int m = 0; m < 4; ++m) _Pragma("unroll") for (int k = 0; k < 2; ++k) dst[m][k] = *(const LAS bf16x8*)(lds + PG8_SA(b, h) + aoff + m * 2048 + k * 1024); } while (0)
; #define PG8_MMA(ai, bj, At, Bt) do { __builtin_amdgcn_s_setprio(1); _Pragma("unroll") for (int m = 0; m < 4; ++m) _Pragma("unroll") for (int n = 0; n < 2; ++n) _Pragma("unroll") for (int k = 0; k < 2; ++k) \
;         acc[ai][bj][m][n] = __builtin_amdgcn_mfma_f32_16x16x32_bf16(Bt[n][k], At[m][k], acc[ai][bj][m][n], 0, 0, 0); __builtin_amdgcn_s_setprio(0); } while (0)
; #define PG8_WAIT_V(n) asm volatile("s_waitcnt vmcnt(" #n ")" ::: "memory")
; #define PG8_WAIT_L(n) asm volatile("s_waitcnt lgkmcnt(" #n ")" ::: "memory")
; #define PG8_BAR __builtin_amdgcn_s_barrier()
; #define PG8_SCHED __builtin_amdgcn_sched_barrier(0)
; template <class Epi, class Sched>
; __device__ __forceinline__ void gemm_stream(LAS unsigned char* lds, const int lda, const int ldb, const Sched& S, const Epi& E, const int wv) {
;     ...
;             PG8_LDA(At, 1, 1); PG8_STAGE(PG8_SB(1, 0), b3, voffB); PG8_STAGE(PG8_SB(1, 1), b3 + hstepB, voffB); PG8_STAGE(PG8_SA(1, 0), a3, voffA);
;             PG8_WAIT_V(8); PG8_WAIT_L(0); PG8_BAR; PG8_MMA(1, 0, At, B0); PG8_MMA(1, 1, At, B1); PG8_BAR; PG8_SCHED;
;         }
;         if (wr == 0) PG8_BAR;
	s_add_i32 s24, s47, s30
	v_lshl_add_u64 v[192:193], v[192:193], 0, s[78:79]
	s_mov_b32 m0, s24
	ds_read_b128 v[176:179], v166 offset:49152
	ds_read_b128 v[180:183], v166 offset:50176
	ds_read_b128 v[184:187], v166 offset:51200
	ds_read_b128 v[188:191], v166 offset:52224
	ds_read_b128 v[200:203], v166 offset:53248
	ds_read_b128 v[204:207], v166 offset:54272
	ds_read_b128 v[208:211], v166 offset:55296
	ds_read_b128 v[212:215], v166 offset:56320
	global_load_lds_dwordx4 v[192:193], off
	s_add_i32 m0, s24, 0x2000
	s_add_u32 s22, s22, 0x20080
	v_lshl_add_u64 v[192:193], v[196:197], 0, s[78:79]
	s_addc_u32 s23, s23, 0
	s_add_i32 s24, s48, s30
	global_load_lds_dwordx4 v[192:193], off
	v_lshl_add_u64 v[192:193], s[22:23], 0, v[148:149]
	s_mov_b32 m0, s24
	s_nop 0
	global_load_lds_dwordx4 v[192:193], off
	v_lshl_add_u64 v[192:193], s[22:23], 0, v[144:145]
	s_add_i32 m0, s24, 0x2000
	s_nop 0
	global_load_lds_dwordx4 v[192:193], off
	v_lshl_add_u64 v[192:193], v[198:199], 0, s[78:79]
	s_mov_b32 m0, s40
	s_nop 0
	global_load_lds_dwordx4 v[192:193], off
	v_lshl_add_u64 v[192:193], v[216:217], 0, s[78:79]
	s_mov_b32 m0, s41
	s_nop 0
	global_load_lds_dwordx4 v[192:193], off
	s_waitcnt vmcnt(8)
	s_waitcnt lgkmcnt(0)
	s_barrier
	s_setprio 1
	v_mfma_f32_16x16x32_bf16 v[60:63], v[128:131], v[176:179], v[60:63]
	v_mfma_f32_16x16x32_bf16 v[56:59], v[136:139], v[176:179], v[56:59]
	v_mfma_f32_16x16x32_bf16 v[44:47], v[128:131], v[184:187], v[44:47]
	v_mfma_f32_16x16x32_bf16 v[40:43], v[136:139], v[184:187], v[40:43]
	v_mfma_f32_16x16x32_bf16 v[28:31], v[128:131], v[200:203], v[28:31]
	v_mfma_f32_16x16x32_bf16 v[24:27], v[136:139], v[200:203], v[24:27]
	v_mfma_f32_16x16x32_bf16 v[12:15], v[128:131], v[208:211], v[12:15]
	v_mfma_f32_16x16x32_bf16 v[8:11], v[136:139], v[208:211], v[8:11]
	v_mfma_f32_16x16x32_bf16 v[60:63], v[132:135], v[180:183], v[60:63]
	v_mfma_f32_16x16x32_bf16 v[56:59], v[140:143], v[180:183], v[56:59]
	v_mfma_f32_16x16x32_bf16 v[44:47], v[132:135], v[188:191], v[44:47]
	v_mfma_f32_16x16x32_bf16 v[40:43], v[140:143], v[188:191], v[40:43]
	v_mfma_f32_16x16x32_bf16 v[28:31], v[132:135], v[204:207], v[28:31]
	v_mfma_f32_16x16x32_bf16 v[24:27], v[140:143], v[204:207], v[24:27]
	v_mfma_f32_16x16x32_bf16 v[12:15], v[132:135], v[212:215], v[12:15]
	v_mfma_f32_16x16x32_bf16 v[8:11], v[140:143], v[212:215], v[8:11]
	v_mfma_f32_16x16x32_bf16 v[52:55], v[156:159], v[176:179], v[52:55]
	v_mfma_f32_16x16x32_bf16 v[48:51], v[168:171], v[176:179], v[48:51]
	v_mfma_f32_16x16x32_bf16 v[36:39], v[156:159], v[184:187], v[36:39]
	v_mfma_f32_16x16x32_bf16 v[32:35], v[168:171], v[184:187], v[32:35]
	v_mfma_f32_16x16x32_bf16 v[20:23], v[156:159], v[200:203], v[20:23]
	v_mfma_f32_16x16x32_bf16 v[16:19], v[168:171], v[200:203], v[16:19]
	v_mfma_f32_16x16x32_bf16 v[4:7], v[156:159], v[208:211], v[4:7]
	v_mfma_f32_16x16x32_bf16 v[0:3], v[168:171], v[208:211], v[0:3]
	v_mfma_f32_16x16x32_bf16 v[52:55], v[160:163], v[180:183], v[52:55]
	v_mfma_f32_16x16x32_bf16 v[48:51], v[172:175], v[180:183], v[48:51]
	v_mfma_f32_16x16x32_bf16 v[36:39], v[160:163], v[188:191], v[36:39]
	v_mfma_f32_16x16x32_bf16 v[32:35], v[172:175], v[188:191], v[32:35]
	v_mfma_f32_16x16x32_bf16 v[20:23], v[160:163], v[204:207], v[20:23]
	v_mfma_f32_16x16x32_bf16 v[16:19], v[172:175], v[204:207], v[16:19]
	v_mfma_f32_16x16x32_bf16 v[4:7], v[160:163], v[212:215], v[4:7]
	v_mfma_f32_16x16x32_bf16 v[0:3], v[172:175], v[212:215], v[0:3]
	s_setprio 0
	s_barrier
	s_add_i32 s46, s46, 2
	s_add_u32 s20, s20, 0x100
	s_addc_u32 s21, s21, 0
	s_add_u32 s13, s13, 0x100
	s_addc_u32 s15, s15, 0
	s_cmp_gt_u32 s46, 29
	s_cbranch_scc0 .LBB0_600
	s_and_b64 vcc, exec, s[6:7]
	s_cbranch_vccz .LBB0_603
	s_barrier
